# v24 with lockstep attention loop (one barrier per tile, no stagger) + GEMM phase prologue requests K-tile 1 together with K-tile 0
# baseline (speedup 1.0000x reference)
; #define PG8_STAGE(bufoff, gbase, voff) do { _Pragma("unroll") for (int _i = 0; _i < 2; ++_i) \
;         __builtin_amdgcn_global_load_lds((const unsigned*)((const char*)(gbase) + (voff)[_i]), (PG8_LAS unsigned*)(lds + (bufoff) + ldsw + _i * 8192), 16, 0, 0); } while (0)
; #define PG8_WAIT_V(n) asm volatile("s_waitcnt vmcnt(" #n ")" ::: "memory")
; #define PG8_BAR __builtin_amdgcn_s_barrier()
; template <class Epi, class Sched, bool ALIGN_EPI = false, bool SP2 = false>
; __device__ __forceinline__ void gemm_phase(PG8_LAS unsigned char* lds, const Gemm g, const Sched& S, const Epi& E) {
;     ...
;     for (int i = 0; i < 2; ++i) { int R, C; stage_rc(tid * 16 + i * 8192, R, C); const int Rb = Epi::PERM ? ((R & ~31) + perm32(R & 31)) : R;
;         voffA[i] = (unsigned)(R * K + C) * 2u; voffB[i] = (unsigned)(Rb * K + C) * 2u; }
;     ...
;     const char* cA = (const char*)g.A + (size_t)cur.pm * tstep; const char* cB = (const char*)g.Bt + (size_t)cur.pn * tstep;
;     S.a_ready(cur);
;     if constexpr (SP2) {
;         PG8_STAGE(PG8_SB(0, 0), cB, voffB); PG8_STAGE(PG8_SB(0, 1), cB + hstep, voffB); PG8_STAGE(PG8_SA(0, 0), cA, voffA); PG8_STAGE(PG8_SA(0, 1), cA + hstep, voffA);
;         if (wr == 1) PG8_BAR;
;         PG8_WAIT_V(2); PG8_BAR;
;         PG8_STAGE(PG8_SB(1, 0), cB + kstep, voffB); PG8_STAGE(PG8_SA(1, 0), cA + kstep, voffA); PG8_STAGE(PG8_SB(1, 1), cB + hstep + kstep, voffB);
;         PG8_WAIT_V(6); PG8_BAR;
.LBB0_672:
	v_bfe_i32 v2, v18, 27, 1
	v_lshlrev_b32_e32 v0, 4, v18
	v_lshrrev_b32_e32 v2, 22, v2
	v_add_u32_e32 v2, v0, v2
	v_and_b32_e32 v2, 0xfffffc00, v2
	v_sub_u32_e32 v2, v0, v2
	v_ashrrev_i32_e32 v1, 31, v18
	v_lshrrev_b32_e32 v3, 4, v2
	v_lshrrev_b32_e32 v1, 26, v1
	v_bitop3_b32 v2, v3, v2, 32 bitop3:0x6c
	v_add_u32_e32 v1, v18, v1
	v_ashrrev_i32_e32 v4, 31, v2
	v_ashrrev_i32_e32 v1, 6, v1
	v_lshrrev_b32_e32 v4, 26, v4
	s_add_u32 s2, s82, s50
	v_lshlrev_b32_e32 v3, 3, v1
	v_add_u32_e32 v4, v2, v4
	s_addc_u32 s3, s83, s51
	v_and_b32_e32 v3, -16, v3
	v_ashrrev_i32_e32 v5, 6, v4
	v_lshlrev_b32_e32 v1, 5, v1
	s_and_b64 s[0:1], exec, s[0:1]
	v_add_u32_e32 v3, v5, v3
	v_and_b32_e32 v12, 32, v1
	v_and_b32_e32 v1, 0xc0, v4
	v_sub_u32_e32 v1, v2, v1
	v_lshlrev_b32_e32 v2, 1, v3
	v_lshrrev_b32_e32 v4, 2, v3
	v_and_b32_e32 v5, 3, v5
	s_mov_b32 s1, 0x7fffffe0
	v_ashrrev_i16_sdwa v1, v213, sext(v1) dst_sel:DWORD dst_unused:UNUSED_PAD src0_sel:DWORD src1_sel:BYTE_0
	v_and_b32_e32 v2, 24, v2
	v_and_b32_e32 v4, 4, v4
	v_and_or_b32 v5, v3, s1, v5
	v_bfe_i32 v13, v1, 0, 16
	v_or3_b32 v2, v5, v4, v2
	v_add_u32_e32 v1, v12, v13
	v_mul_lo_u32 v14, v3, s64
	v_mul_lo_u32 v2, v2, s64
	v_add_u32_e32 v0, 0x2000, v0
	v_add_lshl_u32 v130, v1, v14, 1
	v_add_lshl_u32 v64, v2, v1, 1
	v_ashrrev_i32_e32 v1, 31, v0
	v_lshrrev_b32_e32 v1, 22, v1
	v_add_u32_e32 v1, v0, v1
	v_ashrrev_i32_e32 v1, 10, v1
	v_mul_i32_i24_e32 v2, 0x400, v1
	v_sub_u32_e32 v0, v0, v2
	v_lshrrev_b32_e32 v2, 4, v0
	v_bitop3_b32 v0, v2, v0, 32 bitop3:0x6c
	v_ashrrev_i32_e32 v3, 31, v0
	v_lshrrev_b32_e32 v3, 26, v3
	v_lshlrev_b32_e32 v2, 3, v1
	v_add_u32_e32 v3, v0, v3
	s_cselect_b32 s59, s81, s3
	s_cselect_b32 s60, s80, s2
	s_add_u32 s61, s82, s52
	v_and_b32_e32 v2, -16, v2
	v_ashrrev_i32_e32 v4, 6, v3
	s_addc_u32 s62, s83, s53
	s_ashr_i32 s0, s10, 6
	v_add_u32_e32 v2, v4, v2
	v_lshlrev_b32_e32 v1, 5, v1
	v_and_b32_e32 v4, 3, v4
	s_lshl_b32 s66, s64, 9
	v_and_b32_e32 v15, 32, v1
	v_and_b32_e32 v1, 0xc0, v3
	v_and_or_b32 v4, v2, s1, v4
	s_ashr_i32 s1, s10, 8
	s_lshl_b32 s4, s64, 8
	s_lshl_b32 s65, s0, 10
	s_mul_i32 s3, s66, s40
	v_sub_u32_e32 v0, v0, v1
	v_lshlrev_b32_e32 v1, 1, v2
	v_lshrrev_b32_e32 v3, 2, v2
	s_mul_hi_i32 s2, s66, s40
	s_add_u32 s16, s61, s3
	v_ashrrev_i16_sdwa v0, v213, sext(v0) dst_sel:DWORD dst_unused:UNUSED_PAD src0_sel:DWORD src1_sel:BYTE_0
	v_and_b32_e32 v1, 24, v1
	v_and_b32_e32 v3, 4, v3
	s_addc_u32 s17, s62, s2
	s_add_i32 s76, s65, 0
	v_bfe_i32 v16, v0, 0, 16
	v_or3_b32 v1, v4, v3, v1
	s_add_i32 m0, s76, 0x10000
	v_add_u32_e32 v0, v15, v16
	v_mul_lo_u32 v1, v1, s64
	global_load_lds_dwordx4 v64, s[16:17]
	s_add_i32 m0, s76, 0x12000
	v_add_lshl_u32 v134, v1, v0, 1
	s_add_u32 s2, s16, s4
	global_load_lds_dwordx4 v134, s[16:17]
	s_addc_u32 s3, s17, 0
	s_add_i32 m0, s76, 0x14000
	s_mul_i32 s8, s66, s25
	global_load_lds_dwordx4 v64, s[2:3]
	s_add_i32 m0, s76, 0x16000
	s_mul_hi_i32 s9, s66, s25
	v_mov_b32_e32 v135, v65
	s_add_u32 s8, s60, s8
	v_lshl_add_u64 v[4:5], s[2:3], 0, v[64:65]
	v_lshl_add_u64 v[6:7], s[2:3], 0, v[134:135]
	global_load_lds_dwordx4 v134, s[2:3]
	s_addc_u32 s9, s59, s9
	s_add_i32 s2, s76, 0x2000
	v_mul_lo_u32 v17, v2, s64
	s_mov_b32 m0, s76
	s_add_u32 s22, s8, s4
	v_add_lshl_u32 v132, v0, v17, 1
	global_load_lds_dwordx4 v130, s[8:9]
	s_mov_b32 m0, s2
	s_addc_u32 s23, s9, 0
	s_add_i32 s3, s76, 0x4000
	global_load_lds_dwordx4 v132, s[8:9]
	s_mov_b32 m0, s3
	s_add_i32 s70, s76, 0x6000
	global_load_lds_dwordx4 v130, s[22:23]
	s_mov_b32 m0, s70
	s_cmp_eq_u32 s1, 1
	global_load_lds_dwordx4 v132, s[22:23]
	v_mov_b32_e32 v131, v65
	v_mov_b32_e32 v133, v65
	s_cselect_b64 s[22:23], -1, 0
	v_lshl_add_u64 v[0:1], s[16:17], 0, v[64:65]
	v_lshl_add_u64 v[2:3], s[16:17], 0, v[134:135]
	v_lshl_add_u64 v[8:9], s[8:9], 0, v[130:131]
	v_lshl_add_u64 v[10:11], s[8:9], 0, v[132:133]
	v_writelane_b32 v251, s22, 61
	s_add_i32 m0, s76, 0x18000
	v_lshl_add_u64 v[0:1], v[0:1], 0, s[44:45]
	s_add_i32 s73, s76, 0x8000
	global_load_lds_dwordx4 v[0:1], off
	v_lshl_add_u64 v[0:1], v[2:3], 0, s[44:45]
	s_add_i32 m0, s76, 0x1a000
	s_add_i32 s68, s76, 0xa000
	global_load_lds_dwordx4 v[0:1], off
	v_lshl_add_u64 v[0:1], v[8:9], 0, s[44:45]
	s_mov_b32 m0, s73
	s_nop 0
	global_load_lds_dwordx4 v[0:1], off
	v_lshl_add_u64 v[0:1], v[10:11], 0, s[44:45]
	s_mov_b32 m0, s68
	s_nop 0
	global_load_lds_dwordx4 v[0:1], off
	s_add_i32 m0, s76, 0x1c000
	v_lshl_add_u64 v[0:1], v[4:5], 0, s[44:45]
	global_load_lds_dwordx4 v[0:1], off
	v_lshl_add_u64 v[0:1], v[6:7], 0, s[44:45]
	s_add_i32 m0, s76, 0x1e000
	s_nop 0
	global_load_lds_dwordx4 v[0:1], off
	s_cmp_lg_u32 s1, 1
	s_nop 0
	v_writelane_b32 v251, s23, 62
	s_cbranch_scc1 .LBB0_674
	s_barrier
.LBB0_674:
	s_cmp_eq_u32 s75, 15
	s_mov_b32 s11, 0x40000
	s_cselect_b32 s22, 0x80000, s11
	s_waitcnt vmcnt(8)
	s_barrier
	v_lshrrev_b32_e32 v20, 1, v18
	v_and_b32_e32 v20, 24, v20
	v_and_b32_e32 v19, 15, v18
	v_lshlrev_b32_e32 v21, 1, v20
	v_lshlrev_b32_e32 v18, 2, v18
	s_lshl_b32 s0, s0, 5
	s_lshr_b32 s87, s64, 6
	v_lshl_or_b32 v160, s1, 6, v19
	v_lshl_or_b32 v19, v19, 6, v21
	s_lshl_b32 s1, s1, 13
	v_and_b32_e32 v18, 32, v18
	s_and_b32 s0, s0, 0x60
	v_bitop3_b32 v21, v19, s1, v18 bitop3:0xde
	s_lshl_b32 s1, s0, 7
	s_add_i32 s72, s87, -2
	s_cmpk_lt_u32 s10, 0x100
	s_cselect_b64 s[94:95], -1, 0
	s_lshr_b32 s42, s54, 5
	v_cvt_f32_u32_e32 v0, s42
	s_lshr_b32 s63, s28, 3
	v_or_b32_e32 v168, s0, v20
	s_add_i32 s0, s63, 1
	v_rcp_iflag_f32_e32 v0, v0
	s_ashr_i32 s10, s69, 31
	s_and_b32 s11, s28, 7
	v_writelane_b32 v250, s0, 5
	v_mul_f32_e32 v0, 0x4f7ffffe, v0
	s_add_i32 s0, s24, -1
	v_cvt_u32_f32_e32 v0, v0
	s_cmp_lt_u32 s0, 2
	v_bitop3_b32 v161, v19, s1, v18 bitop3:0xde
	s_cselect_b64 s[0:1], -1, 0
	v_writelane_b32 v251, s0, 63
	s_add_u32 s22, s82, s22
	s_addc_u32 s23, s83, 0
	v_writelane_b32 v250, s1, 0
	v_readfirstlane_b32 s1, v0
	v_add_u32_e32 v0, v14, v12
	s_sub_i32 s0, 0, s42
	v_add_lshl_u32 v0, v0, v13, 1
	v_mov_b32_e32 v1, v65
	s_waitcnt vmcnt(6)
	s_mul_i32 s0, s0, s1
	v_lshl_add_u64 v[136:137], s[4:5], 0, v[0:1]
	v_add_u32_e32 v0, v17, v15
	s_mul_hi_u32 s0, s1, s0
	v_add_lshl_u32 v0, v0, v16, 1
	s_mov_b32 s71, 0
	s_mov_b32 s29, s5
	s_add_i32 s0, s1, s0
	v_lshl_add_u64 v[138:139], s[4:5], 0, v[0:1]
	v_add_u32_e32 v169, 0, v21
	s_barrier
	v_writelane_b32 v250, s0, 3
	s_branch .LBB0_677

; __device__ __forceinline__ unsigned pk2(float lo, float hi) { return pg8::cvt_pk_bf16(lo, hi); }
; __device__ __forceinline__ void prompt_unit(LAS unsigned char* lds, const Ptrs& P, int qloc0, int qglob0, int kloc0, int kglob0, int h, int qb) {
;     ...
;     l += __shfl_xor(l, 32);
;     const float inv = 1.0f / l;
;     bf16_t* orow = P.ATT + (size_t)(qglob0 + 32 * wid + r32) * 1024 + h * 64;
; #pragma unroll
;     for (int db = 0; db < 2; ++db)
; #pragma unroll
;         for (int g = 0; g < 4; ++g) { u32x2 w; w.x = pk2(o[db][4 * g] * inv, o[db][4 * g + 1] * inv); w.y = pk2(o[db][4 * g + 2] * inv, o[db][4 * g + 3] * inv);
;             *(u32x2*)(orow + 32 * db + 8 * g + 4 * hi) = w; }
.LBB0_1142:
	v_cmp_lt_i32_e32 vcc, v99, v100
	s_or_b32 s27, s27, s24
	s_nop 0
	v_cndmask_b32_e32 v32, v98, v99, vcc
	v_lshlrev_b32_e32 v32, 2, v32
	ds_bpermute_b32 v32, v32, v135
	s_barrier
	s_waitcnt lgkmcnt(0)
	v_lshlrev_b32_e32 v64, 3, v142
	s_mov_b64 s[66:67], 0
	v_add_f32_e32 v32, v135, v32
	v_div_scale_f32 v33, s[38:39], v32, v32, 1.0
	v_rcp_f32_e32 v34, v33
	s_nop 0
	v_fma_f32 v35, -v33, v34, 1.0
	v_fmac_f32_e32 v34, v35, v34
	v_div_scale_f32 v35, vcc, 1.0, v32, 1.0
	v_mul_f32_e32 v36, v35, v34
	v_fma_f32 v37, -v33, v36, v35
	v_fmac_f32_e32 v36, v37, v34
	v_fma_f32 v33, -v33, v36, v35
	v_div_fmas_f32 v33, v33, v34, v36
	v_div_fixup_f32 v34, v33, v32, 1.0
	v_add_u32_e32 v32, s27, v143
	v_ashrrev_i32_e32 v33, 31, v32
	v_lshlrev_b64 v[32:33], 11, v[32:33]
	v_lshl_add_u64 v[32:33], s[36:37], 0, v[32:33]
	v_lshl_add_u64 v[32:33], v[32:33], 0, v[64:65]
	v_lshl_add_u64 v[32:33], v[32:33], 0, v[64:65]
	v_mul_f32_e32 v0, v0, v34
	v_mul_f32_e32 v1, v1, v34
	v_mul_f32_e32 v2, v2, v34
	v_mul_f32_e32 v3, v3, v34
	v_mul_f32_e32 v4, v4, v34
	v_mul_f32_e32 v5, v5, v34
	v_mul_f32_e32 v6, v6, v34
	v_mul_f32_e32 v7, v7, v34
	v_mul_f32_e32 v8, v8, v34
	v_mul_f32_e32 v9, v9, v34
	v_mul_f32_e32 v10, v10, v34
	v_mul_f32_e32 v11, v11, v34
	v_mul_f32_e32 v12, v12, v34
	v_mul_f32_e32 v13, v13, v34
	v_mul_f32_e32 v14, v14, v34
	v_mul_f32_e32 v15, v15, v34
	v_mul_f32_e32 v16, v16, v34
	v_mul_f32_e32 v17, v17, v34
	v_mul_f32_e32 v18, v18, v34
	v_mul_f32_e32 v19, v19, v34
	v_mul_f32_e32 v20, v20, v34
	v_mul_f32_e32 v21, v21, v34
	v_mul_f32_e32 v22, v22, v34
	v_mul_f32_e32 v23, v23, v34
	v_mul_f32_e32 v24, v24, v34
	v_mul_f32_e32 v25, v25, v34
	v_mul_f32_e32 v26, v26, v34
	v_mul_f32_e32 v27, v27, v34
	v_mul_f32_e32 v28, v28, v34
	v_mul_f32_e32 v29, v29, v34
	v_mul_f32_e32 v30, v30, v34
	v_mul_f32_e32 v31, v31, v34
	v_cvt_pk_bf16_f32 v36, v16, v17
	v_cvt_pk_bf16_f32 v37, v18, v19
	v_cvt_pk_bf16_f32 v38, v20, v21
	v_cvt_pk_bf16_f32 v39, v22, v23
	s_nop 1
	v_permlane32_swap_b32_e32 v36, v38
	v_permlane32_swap_b32_e32 v37, v39
	global_store_dwordx4 v[32:33], v[36:39], off
	v_cvt_pk_bf16_f32 v40, v24, v25
	v_cvt_pk_bf16_f32 v41, v26, v27
	v_cvt_pk_bf16_f32 v42, v28, v29
	v_cvt_pk_bf16_f32 v43, v30, v31
	s_nop 1
	v_permlane32_swap_b32_e32 v40, v42
	v_permlane32_swap_b32_e32 v41, v43
	global_store_dwordx4 v[32:33], v[40:43], off offset:32
	v_cvt_pk_bf16_f32 v44, v0, v1
	v_cvt_pk_bf16_f32 v45, v2, v3
	v_cvt_pk_bf16_f32 v46, v4, v5
	v_cvt_pk_bf16_f32 v47, v6, v7
	s_nop 1
	v_permlane32_swap_b32_e32 v44, v46
	v_permlane32_swap_b32_e32 v45, v47
	global_store_dwordx4 v[32:33], v[44:47], off offset:64
	v_cvt_pk_bf16_f32 v48, v8, v9
	v_cvt_pk_bf16_f32 v49, v10, v11
	v_cvt_pk_bf16_f32 v50, v12, v13
	v_cvt_pk_bf16_f32 v51, v14, v15
	s_nop 1
	v_permlane32_swap_b32_e32 v48, v50
	v_permlane32_swap_b32_e32 v49, v51
	global_store_dwordx4 v[32:33], v[48:51], off offset:96
	s_and_b64 vcc, exec, s[64:65]
	s_cbranch_vccnz .LBB0_1139

; #define LAS __attribute__((address_space(3)))
; __device__ __forceinline__ void prompt_unit(LAS unsigned char* lds, const Ptrs& P, int qloc0, int qglob0, int kloc0, int kglob0, int h, int qb) {
;     ...
;     *(LAS u32x4*)(lds + k_w) = kreg; if (tid < 256) *(LAS u32x4*)(lds + r_w) = rreg;
;     *(LAS u32x2*)(lds + v_w) = (u32x2){vreg.x, vreg.y}; *(LAS u32x2*)(lds + v_w + 16) = (u32x2){vreg.z, vreg.w};
;     __syncthreads();
;     float m = -1e30f, l = 0.f; f32x16 o[2];
; #pragma unroll
;     for (int r = 0; r < 16; ++r) { o[0][r] = 0.f; o[1][r] = 0.f; }
;     for (int j = 0; j < NTL; ++j) {
;         const bool more = j + 1 < NTL;
;         if (more) { kreg = *(const u32x4*)(kn_src + (size_t)(j + 1) * 64 * 1024); vreg = *(const u32x4*)(vt_src + (j + 1) * 64); if (tid < 256) rreg = *(const u32x4*)(kr_src + (size_t)(j + 1) * 64 * 32); }
;         if (j <= cq) {
;             const LAS unsigned char* buf = lds + (j & 1) * BUFB;
.LBB0_1149:
	s_or_b64 exec, exec, s[64:65]
	s_xor_b64 s[64:65], s[66:67], -1
	s_movk_i32 s67, 0x90
	v_mul_lo_u32 v4, v12, s67
	v_lshlrev_b32_e32 v6, 3, v16
	v_and_b32_e32 v5, 0x60, v8
	v_and_or_b32 v4, v6, 8, v4
	v_add_u32_e32 v148, v4, v5
	v_add_u32_e32 v4, 0, v148
	v_add_u32_e32 v4, 0x3000, v4
	s_lshl_b32 s66, s68, 2
	s_ashr_i32 s68, s69, 7
	s_waitcnt vmcnt(4)
	ds_write2_b64 v4, v[110:111], v[112:113] offset0:128 offset1:130
	v_lshlrev_b32_e32 v2, 4, v16
	s_add_i32 s69, s68, s66
	s_or_b32 s70, s66, 3
	v_mad_i64_i32 v[0:1], s[66:67], v12, s77, 0
	v_and_b32_e32 v2, 0x70, v2
	v_or_b32_e32 v0, v0, v2
	v_lshl_add_u64 v[136:137], s[40:41], 0, v[0:1]
	v_add_u32_e32 v0, s9, v13
	v_ashrrev_i32_e32 v1, 31, v0
	v_lshlrev_b64 v[0:1], 6, v[0:1]
	v_lshl_or_b32 v0, v9, 4, v0
	v_lshl_add_u64 v[138:139], s[96:97], 0, v[0:1]
	v_add_u32_e32 v0, s2, v12
	v_ashrrev_i32_e32 v1, 31, v0
	v_lshlrev_b64 v[0:1], 11, v[0:1]
	v_or_b32_e32 v0, v0, v2
	v_mul_u32_u24_e32 v147, 0xd0, v17
	v_mul_u32_u24_e32 v145, 0x90, v17
	v_add_u32_e32 v149, 0, v64
	v_lshl_add_u64 v[140:141], s[42:43], 0, v[0:1]
	s_mov_b64 s[66:67], 0x100
	v_lshl_add_u64 v[136:137], v[136:137], 0, s[66:67]
	s_mov_b64 s[66:67], 0x2000
	v_lshl_add_u64 v[138:139], v[138:139], 0, s[66:67]
	s_mov_b64 s[66:67], 0x40000
	s_mov_b32 s71, 0
	v_lshl_add_u64 v[140:141], v[140:141], 0, s[66:67]
	v_mov_b32_e32 v16, v65
	v_mov_b32_e32 v17, v65
	v_mov_b32_e32 v18, v65
	v_mov_b32_e32 v19, v65
	v_mov_b32_e32 v20, v65
	v_mov_b32_e32 v21, v65
	v_mov_b32_e32 v22, v65
	v_mov_b32_e32 v23, v65
	v_mov_b32_e32 v24, v65
	v_mov_b32_e32 v25, v65
	v_mov_b32_e32 v26, v65
	v_mov_b32_e32 v27, v65
	v_mov_b32_e32 v28, v65
	v_mov_b32_e32 v29, v65
	v_mov_b32_e32 v30, v65
	v_mov_b32_e32 v31, v65
	v_mov_b32_e32 v0, v65
	v_mov_b32_e32 v1, v65
	v_mov_b32_e32 v2, v65
	v_mov_b32_e32 v3, v65
	v_mov_b32_e32 v4, v65
	v_mov_b32_e32 v5, v65
	v_mov_b32_e32 v6, v65
	v_mov_b32_e32 v7, v65
	v_mov_b32_e32 v8, v65
	v_mov_b32_e32 v9, v65
	v_mov_b32_e32 v10, v65
	v_mov_b32_e32 v11, v65
	v_mov_b32_e32 v12, v65
	v_mov_b32_e32 v13, v65
	v_mov_b32_e32 v14, v65
	v_mov_b32_e32 v15, v65
	v_mov_b32_e32 v144, 0xf149f2ca
	v_mov_b32_e32 v135, 0
	s_waitcnt lgkmcnt(0)
	s_barrier
	s_mov_b32 s72, 0
.LBB0_1151:
	s_add_i32 s66, s72, 0x5800
	s_cmp_ge_u32 s66, 0x10800
	s_cselect_b32 s66, 0, s66
	v_add_u32_e32 v32, s66, v134
	v_add_u32_e32 v33, s66, v148
	v_add_u32_e32 v34, s66, v146
	v_add_u32_e32 v33, 0x3000, v33
	s_add_i32 s66, s71, 2
	s_cmp_gt_u32 s66, s70
	s_cbranch_scc1 .Latt_wait_all
	s_waitcnt vmcnt(2)
	s_branch .Latt_wait_done

; __device__ __forceinline__ unsigned pk2(float lo, float hi) { return pg8::cvt_pk_bf16(lo, hi); }
; __device__ __forceinline__ void tile_core(const bf16x8 (&kf)[2][6], const bf16x8 (&vf)[2][4], const bf16x8 (&qf)[6], float& m, float& l, f32x16 (&o)[2], int nvalid, int hi) {
;     ...
;     if (__any(rm > m + 8.0f)) { const float mn = fmaxf(m, rm), f = __builtin_amdgcn_exp2f(m - mn); l *= f; m = mn;
; #pragma unroll
;         for (int r = 0; r < 16; ++r) { o[0][r] *= f; o[1][r] *= f; } }
;     float s = 0.f;
; #pragma unroll
;     for (int r = 0; r < 16; ++r) { p0[r] = __builtin_amdgcn_exp2f(p0[r] - m); p1[r] = __builtin_amdgcn_exp2f(p1[r] - m); s += p0[r] + p1[r]; }
;     l += s;
;     bf16x8 pa[4];
;     { u32x4 w;
;       w = (u32x4){pk2(p0[0], p0[1]), pk2(p0[2], p0[3]), pk2(p0[4], p0[5]), pk2(p0[6], p0[7])}; pa[0] = __builtin_bit_cast(bf16x8, w);
;       w = (u32x4){pk2(p0[8], p0[9]), pk2(p0[10], p0[11]), pk2(p0[12], p0[13]), pk2(p0[14], p0[15])}; pa[1] = __builtin_bit_cast(bf16x8, w);
;       w = (u32x4){pk2(p1[0], p1[1]), pk2(p1[2], p1[3]), pk2(p1[4], p1[5]), pk2(p1[6], p1[7])}; pa[2] = __builtin_bit_cast(bf16x8, w);
;       w = (u32x4){pk2(p1[8], p1[9]), pk2(p1[10], p1[11]), pk2(p1[12], p1[13]), pk2(p1[14], p1[15])}; pa[3] = __builtin_bit_cast(bf16x8, w); }
; #pragma unroll
;     for (int db = 0; db < 2; ++db)
; #pragma unroll
;         for (int s4 = 0; s4 < 4; ++s4) o[db] = __builtin_amdgcn_mfma_f32_32x32x16_bf16(vf[db][s4], pa[s4], o[db], 0, 0, 0);
.LBB0_1156:
	s_waitcnt lgkmcnt(4)
	v_sub_f32_e32 v48, v48, v144
	v_sub_f32_e32 v49, v49, v144
	v_sub_f32_e32 v50, v50, v144
	v_sub_f32_e32 v51, v51, v144
	v_sub_f32_e32 v52, v52, v144
	v_sub_f32_e32 v53, v53, v144
	v_sub_f32_e32 v54, v54, v144
	v_sub_f32_e32 v55, v55, v144
	v_sub_f32_e32 v56, v56, v144
	v_sub_f32_e32 v57, v57, v144
	v_sub_f32_e32 v58, v58, v144
	v_sub_f32_e32 v59, v59, v144
	v_sub_f32_e32 v60, v60, v144
	v_sub_f32_e32 v61, v61, v144
	v_sub_f32_e32 v62, v62, v144
	v_sub_f32_e32 v63, v63, v144
	v_exp_f32_e32 v48, v48
	v_exp_f32_e32 v49, v49
	v_exp_f32_e32 v50, v50
	v_exp_f32_e32 v51, v51
	v_exp_f32_e32 v52, v52
	v_exp_f32_e32 v53, v53
	v_exp_f32_e32 v54, v54
	v_exp_f32_e32 v55, v55
	v_exp_f32_e32 v56, v56
	v_exp_f32_e32 v57, v57
	v_exp_f32_e32 v58, v58
	v_exp_f32_e32 v59, v59
	v_exp_f32_e32 v60, v60
	v_exp_f32_e32 v61, v61
	v_exp_f32_e32 v62, v62
	v_exp_f32_e32 v63, v63
	v_sub_f32_e32 v32, v32, v144
	v_sub_f32_e32 v33, v33, v144
	v_sub_f32_e32 v34, v34, v144
	v_sub_f32_e32 v35, v35, v144
	v_sub_f32_e32 v36, v36, v144
	v_sub_f32_e32 v37, v37, v144
	v_sub_f32_e32 v38, v38, v144
	v_sub_f32_e32 v39, v39, v144
	v_cvt_pk_bf16_f32 v184, v48, v49
	v_cvt_pk_bf16_f32 v185, v50, v51
	v_cvt_pk_bf16_f32 v186, v52, v53
	v_cvt_pk_bf16_f32 v187, v54, v55
	v_cvt_pk_bf16_f32 v188, v56, v57
	v_cvt_pk_bf16_f32 v189, v58, v59
	v_cvt_pk_bf16_f32 v190, v60, v61
	v_cvt_pk_bf16_f32 v191, v62, v63
	v_sub_f32_e32 v40, v40, v144
	v_sub_f32_e32 v41, v41, v144
	v_sub_f32_e32 v42, v42, v144
	v_sub_f32_e32 v43, v43, v144
	v_sub_f32_e32 v44, v44, v144
	v_sub_f32_e32 v45, v45, v144
	v_sub_f32_e32 v46, v46, v144
	v_sub_f32_e32 v47, v47, v144
	s_waitcnt lgkmcnt(0)
	v_mfma_f32_32x32x16_bf16 v[16:31], v[130:133], v[184:187], v[16:31]
	v_exp_f32_e32 v32, v32
	v_exp_f32_e32 v33, v33
	v_exp_f32_e32 v34, v34
	v_exp_f32_e32 v35, v35
	v_mfma_f32_32x32x16_bf16 v[0:15], v[118:121], v[184:187], v[0:15]
	v_exp_f32_e32 v36, v36
	v_exp_f32_e32 v37, v37
	v_exp_f32_e32 v38, v38
	v_exp_f32_e32 v39, v39
	v_mfma_f32_32x32x16_bf16 v[16:31], v[126:129], v[188:191], v[16:31]
	v_exp_f32_e32 v40, v40
	v_exp_f32_e32 v41, v41
	v_exp_f32_e32 v42, v42
	v_exp_f32_e32 v43, v43
	v_mfma_f32_32x32x16_bf16 v[0:15], v[110:113], v[188:191], v[0:15]
	v_exp_f32_e32 v44, v44
	v_exp_f32_e32 v45, v45
	v_exp_f32_e32 v46, v46
	v_exp_f32_e32 v47, v47
	v_add_f32_e32 v150, v48, v49
	v_add_f32_e32 v151, v50, v51
	v_add_f32_e32 v152, v52, v53
	v_add_f32_e32 v153, v54, v55
	v_add_f32_e32 v154, v56, v57
	v_add_f32_e32 v155, v58, v59
	v_add_f32_e32 v156, v60, v61
	v_add_f32_e32 v157, v62, v63
	v_cvt_pk_bf16_f32 v192, v32, v33
	v_cvt_pk_bf16_f32 v193, v34, v35
	v_cvt_pk_bf16_f32 v194, v36, v37
	v_cvt_pk_bf16_f32 v195, v38, v39
	v_cvt_pk_bf16_f32 v196, v40, v41
	v_cvt_pk_bf16_f32 v197, v42, v43
	v_cvt_pk_bf16_f32 v198, v44, v45
	v_cvt_pk_bf16_f32 v199, v46, v47
	v_add_f32_e32 v158, v32, v33
	v_add_f32_e32 v159, v34, v35
	v_mfma_f32_32x32x16_bf16 v[16:31], v[122:125], v[192:195], v[16:31]
	v_add_f32_e32 v160, v36, v37
	v_add_f32_e32 v161, v38, v39
	v_add_f32_e32 v168, v40, v41
	v_add_f32_e32 v169, v42, v43
	v_add_f32_e32 v170, v44, v45
	v_add_f32_e32 v171, v46, v47
	v_mfma_f32_32x32x16_bf16 v[0:15], v[106:109], v[192:195], v[0:15]
	v_add_f32_e32 v150, v150, v158
	v_add_f32_e32 v151, v151, v159
	v_add_f32_e32 v152, v152, v160
	v_add_f32_e32 v153, v153, v161
	v_add_f32_e32 v154, v154, v168
	v_add_f32_e32 v155, v155, v169
	v_mfma_f32_32x32x16_bf16 v[16:31], v[114:117], v[196:199], v[16:31]
	v_add_f32_e32 v156, v156, v170
	v_add_f32_e32 v157, v157, v171
	v_add_f32_e32 v150, v150, v151
	v_add_f32_e32 v152, v152, v153
	v_add_f32_e32 v154, v154, v155
	v_add_f32_e32 v156, v156, v157
	v_mfma_f32_32x32x16_bf16 v[0:15], v[102:105], v[196:199], v[0:15]
	v_add_f32_e32 v150, v150, v152
	v_add_f32_e32 v154, v154, v156
	v_add_f32_e32 v150, v150, v154
	v_add_f32_e32 v135, v135, v150
	s_branch .LBB0_1157
.Latt_skip_tile:
	s_waitcnt lgkmcnt(0)
.LBB0_1157:
	s_add_i32 s71, s71, 1
	s_add_i32 s72, s72, 0x5800
	s_cmp_ge_u32 s72, 0x10800
	s_cselect_b32 s72, 0, s72
	s_cmp_eq_u32 s70, s71
	s_barrier
	s_cbranch_scc0 .LBB0_1151
